# v14 + one static s_setprio 1 for waves 0-3 (older half) during the attention phase
# speedup vs baseline: 1.0021x; 1.0021x over previous
.LBB0_729:
	s_or_b64 exec, exec, s[8:9]
	s_mov_b64 s[10:11], s[96:97]
	s_waitcnt lgkmcnt(0)
	s_barrier
	v_readfirstlane_b32 s76, v193
	s_nop 3
	s_lshr_b32 s76, s76, 6
	s_cmp_lt_u32 s76, 4
	s_cbranch_scc0 .Lnoprio_att
	s_setprio 1
